# nt also on the final y stores (last row pass), the f32 cache-copy stores and the rolling-cache input loads in cache_tail
# speedup vs baseline: 1.0427x; 1.0088x over previous
.LBB0_421:
	s_or_b64 exec, exec, s[26:27]
	v_lshlrev_b32_e32 v2, 8, v46
	v_lshlrev_b32_e32 v3, 3, v46
	s_mov_b64 s[26:27], -1
	s_cmpk_gt_i32 s38, 0x1fff
	v_and_b32_e32 v38, 0xe00, v2
	v_and_b32_e32 v34, 8, v3
	v_and_b32_e32 v40, 0x800, v2
	v_and_b32_e32 v36, 56, v3
	s_cbranch_scc0 .LBB0_431
	s_load_dwordx4 s[28:31], s[20:21], 0x10
	s_add_i32 s26, s38, 0xffffe000
	v_lshlrev_b32_e32 v2, 2, v46
	v_lshl_add_u32 v2, s26, 10, v2
	v_ashrrev_i32_e32 v3, 31, v2
	v_lshlrev_b64 v[2:3], 2, v[2:3]
	s_waitcnt lgkmcnt(0)
	v_lshl_add_u64 v[42:43], s[28:29], 0, v[2:3]
	v_lshl_add_u64 v[44:45], s[30:31], 0, v[2:3]
	global_load_dwordx4 v[26:29], v[42:43], off nt
	global_load_dwordx4 v[22:25], v[42:43], off offset:1024 nt
	global_load_dwordx4 v[30:33], v[44:45], off nt
	global_load_dwordx4 v[18:21], v[44:45], off offset:1024 nt
	global_load_dwordx4 v[10:13], v[42:43], off offset:2048 nt
	global_load_dwordx4 v[6:9], v[42:43], off offset:3072 nt
	global_load_dwordx4 v[14:17], v[44:45], off offset:2048 nt
	global_load_dwordx4 v[2:5], v[44:45], off offset:3072 nt
	v_mov_b32_e32 v41, v35
	v_lshl_add_u32 v47, s26, 8, v46
	v_mov_b32_e32 v39, v35
	v_lshl_add_u64 v[42:43], s[8:9], 0, v[40:41]
	v_lshlrev_b32_e32 v41, 2, v47
	v_lshl_add_u64 v[44:45], s[6:7], 0, v[38:39]
	v_ashrrev_i32_e32 v39, 12, v47
	v_lshrrev_b32_e32 v49, 5, v47
	v_bfe_u32 v54, v41, 6, 1
	v_bfe_u32 v49, v49, 5, 2
	v_lshl_or_b32 v54, v39, 1, v54
	v_mad_i32_i24 v54, v54, 5, v49
	v_ashrrev_i32_e32 v55, 31, v54
	v_bfe_u32 v52, v47, 5, 5
	v_lshlrev_b64 v[54:55], 12, v[54:55]
	v_mov_b32_e32 v51, v35
	v_mov_b32_e32 v53, v35
	v_lshlrev_b32_e32 v50, 4, v52
	v_lshlrev_b32_e32 v52, 6, v52
	v_lshl_add_u64 v[56:57], v[44:45], 0, v[54:55]
	v_lshl_add_u64 v[54:55], v[42:43], 0, v[54:55]
	v_lshl_add_u64 v[50:51], v[56:57], 0, v[50:51]
	v_lshl_add_u64 v[52:53], v[54:55], 0, v[52:53]
	v_bfe_u32 v48, v47, 5, 7
	v_mov_b32_e32 v37, v35
	v_lshl_add_u64 v[50:51], v[50:51], 0, v[34:35]
	v_cmp_lt_u32_e32 vcc, 31, v48
	v_lshl_add_u64 v[52:53], v[52:53], 0, v[36:37]
	s_waitcnt vmcnt(0)
	v_mov_b32_e32 v54, v26
	v_mov_b32_e32 v55, v22
	v_mov_b32_e32 v56, v30
	v_mov_b32_e32 v57, v18
	v_mov_b32_e32 v58, v10
	v_mov_b32_e32 v59, v6
	v_mov_b32_e32 v60, v14
	v_mov_b32_e32 v61, v2
	v_bfe_u32 v49, v26, 16, 1
	v_bfe_u32 v63, v28, 16, 1
	v_pk_add_f32 v[54:55], v[54:55], v[56:57]
	v_bfe_u32 v62, v27, 16, 1
	v_bfe_u32 v64, v29, 16, 1
	v_bfe_u32 v65, v30, 16, 1
	v_bfe_u32 v67, v32, 16, 1
	v_pk_add_f32 v[56:57], v[58:59], v[60:61]
	v_add3_u32 v49, v26, v49, s36
	v_add3_u32 v59, v28, v63, s36
	v_add_f32_e32 v54, 0, v54
	v_bfe_u32 v66, v31, 16, 1
	v_bfe_u32 v68, v33, 16, 1
	v_add3_u32 v58, v27, v62, s36
	v_add3_u32 v60, v29, v64, s36
	v_add3_u32 v61, v30, v65, s36
	v_add3_u32 v63, v32, v67, s36
	v_lshrrev_b32_e32 v49, 16, v49
	v_lshrrev_b32_e32 v59, 16, v59
	v_add_f32_e32 v65, v54, v55
	v_add3_u32 v62, v31, v66, s36
	v_add3_u32 v64, v33, v68, s36
	v_lshrrev_b32_e32 v61, 16, v61
	v_lshrrev_b32_e32 v63, 16, v63
	v_and_or_b32 v54, v58, s37, v49
	v_and_or_b32 v55, v60, s37, v59
	v_add_f32_e32 v49, v65, v56
	v_and_or_b32 v58, v62, s37, v61
	v_and_or_b32 v59, v64, s37, v63
	v_add_f32_e32 v49, v49, v57
	global_store_dwordx2 v[50:51], v[54:55], off sc1
	global_store_dwordx2 v[52:53], v[58:59], off sc1
	s_and_saveexec_b64 s[26:27], vcc
	s_cbranch_execz .LBB0_424
	v_lshl_or_b32 v39, v39, 7, v48
	v_subrev_u32_e32 v48, 32, v39
	v_ashrrev_i32_e32 v49, 31, v48
	v_and_b32_e32 v41, 0x7c, v41
	v_lshlrev_b64 v[48:49], 9, v[48:49]
	v_lshl_or_b32 v48, v41, 2, v48
	v_lshl_add_u64 v[50:51], s[10:11], 0, v[48:49]
	global_store_dwordx4 v[50:51], v[26:29], off sc0 sc1 nt
	s_nop 1
	v_lshl_add_u64 v[26:27], s[12:13], 0, v[48:49]
	global_store_dwordx4 v[26:27], v[30:33], off sc0 sc1 nt
	s_nop 1
.LBB0_424:
	s_or_b64 exec, exec, s[26:27]
	v_add_u32_e32 v29, 64, v47
	v_lshlrev_b32_e32 v27, 2, v29
	v_ashrrev_i32_e32 v26, 12, v29
	v_lshrrev_b32_e32 v30, 5, v29
	v_bfe_u32 v31, v27, 6, 1
	v_lshl_or_b32 v31, v26, 1, v31
	v_bfe_u32 v30, v30, 5, 2
	v_mad_i32_i24 v30, v31, 5, v30
	v_ashrrev_i32_e32 v31, 31, v30
	v_bfe_u32 v39, v22, 16, 1
	v_bfe_u32 v28, v29, 5, 7
	v_lshlrev_b64 v[30:31], 12, v[30:31]
	v_bfe_u32 v29, v29, 5, 5
	v_add3_u32 v39, v22, v39, s36
	v_bfe_u32 v41, v23, 16, 1
	v_lshl_add_u64 v[32:33], v[44:45], 0, v[30:31]
	v_lshlrev_b32_e32 v48, 4, v29
	v_mov_b32_e32 v49, v35
	v_lshrrev_b32_e32 v39, 16, v39
	v_add3_u32 v41, v23, v41, s36
	v_lshl_add_u64 v[32:33], v[32:33], 0, v[48:49]
	v_and_or_b32 v48, v41, s37, v39
	v_bfe_u32 v39, v24, 16, 1
	v_add3_u32 v39, v24, v39, s36
	v_bfe_u32 v41, v25, 16, 1
	v_lshrrev_b32_e32 v39, 16, v39
	v_add3_u32 v41, v25, v41, s36
	v_lshl_add_u64 v[32:33], v[32:33], 0, v[34:35]
	v_and_or_b32 v49, v41, s37, v39
	global_store_dwordx2 v[32:33], v[48:49], off sc1
	v_lshl_add_u64 v[30:31], v[42:43], 0, v[30:31]
	v_lshlrev_b32_e32 v32, 6, v29
	v_mov_b32_e32 v33, v35
	v_bfe_u32 v29, v18, 16, 1
	v_lshl_add_u64 v[30:31], v[30:31], 0, v[32:33]
	v_add3_u32 v29, v18, v29, s36
	v_bfe_u32 v32, v19, 16, 1
	v_lshrrev_b32_e32 v29, 16, v29
	v_add3_u32 v32, v19, v32, s36
	v_and_or_b32 v32, v32, s37, v29
	v_bfe_u32 v29, v20, 16, 1
	v_add3_u32 v29, v20, v29, s36
	v_bfe_u32 v33, v21, 16, 1
	v_lshrrev_b32_e32 v29, 16, v29
	v_add3_u32 v33, v21, v33, s36
	v_lshl_add_u64 v[30:31], v[30:31], 0, v[36:37]
	v_and_or_b32 v33, v33, s37, v29
	v_cmp_lt_u32_e32 vcc, 31, v28
	global_store_dwordx2 v[30:31], v[32:33], off sc1
	s_and_saveexec_b64 s[26:27], vcc
	s_cbranch_execz .LBB0_426
	v_lshl_or_b32 v26, v26, 7, v28
	v_subrev_u32_e32 v26, 32, v26
	v_and_b32_e32 v29, 0x7c, v27
	v_ashrrev_i32_e32 v27, 31, v26
	v_lshlrev_b64 v[26:27], 9, v[26:27]
	v_lshl_or_b32 v26, v29, 2, v26
	v_lshl_add_u64 v[28:29], s[10:11], 0, v[26:27]
	global_store_dwordx4 v[28:29], v[22:25], off sc0 sc1 nt
	s_nop 1
	v_lshl_add_u64 v[22:23], s[12:13], 0, v[26:27]
	global_store_dwordx4 v[22:23], v[18:21], off sc0 sc1 nt
	s_nop 1
.LBB0_426:
	s_or_b64 exec, exec, s[26:27]
	v_add_u32_e32 v21, 0x80, v47
	v_lshlrev_b32_e32 v19, 2, v21
	v_ashrrev_i32_e32 v18, 12, v21
	v_lshrrev_b32_e32 v22, 5, v21
	v_bfe_u32 v23, v19, 6, 1
	v_lshl_or_b32 v23, v18, 1, v23
	v_bfe_u32 v22, v22, 5, 2
	v_mad_i32_i24 v22, v23, 5, v22
	v_ashrrev_i32_e32 v23, 31, v22
	v_bfe_u32 v20, v21, 5, 7
	v_lshlrev_b64 v[22:23], 12, v[22:23]
	v_bfe_u32 v21, v21, 5, 5
	v_lshl_add_u64 v[24:25], v[44:45], 0, v[22:23]
	v_lshlrev_b32_e32 v26, 4, v21
	v_mov_b32_e32 v27, v35
	v_lshl_add_u64 v[24:25], v[24:25], 0, v[26:27]
	v_bfe_u32 v26, v10, 16, 1
	v_add3_u32 v26, v10, v26, s36
	v_bfe_u32 v27, v11, 16, 1
	v_lshrrev_b32_e32 v26, 16, v26
	v_add3_u32 v27, v11, v27, s36
	v_and_or_b32 v26, v27, s37, v26
	v_bfe_u32 v27, v12, 16, 1
	v_add3_u32 v27, v12, v27, s36
	v_bfe_u32 v28, v13, 16, 1
	v_lshrrev_b32_e32 v27, 16, v27
	v_add3_u32 v28, v13, v28, s36
	v_lshl_add_u64 v[24:25], v[24:25], 0, v[34:35]
	v_and_or_b32 v27, v28, s37, v27
	global_store_dwordx2 v[24:25], v[26:27], off sc1
	v_lshl_add_u64 v[22:23], v[42:43], 0, v[22:23]
	v_lshlrev_b32_e32 v24, 6, v21
	v_mov_b32_e32 v25, v35
	v_bfe_u32 v21, v14, 16, 1
	v_lshl_add_u64 v[22:23], v[22:23], 0, v[24:25]
	v_add3_u32 v21, v14, v21, s36
	v_bfe_u32 v24, v15, 16, 1
	v_lshrrev_b32_e32 v21, 16, v21
	v_add3_u32 v24, v15, v24, s36
	v_and_or_b32 v24, v24, s37, v21
	v_bfe_u32 v21, v16, 16, 1
	v_add3_u32 v21, v16, v21, s36
	v_bfe_u32 v25, v17, 16, 1
	v_lshrrev_b32_e32 v21, 16, v21
	v_add3_u32 v25, v17, v25, s36
	v_lshl_add_u64 v[22:23], v[22:23], 0, v[36:37]
	v_and_or_b32 v25, v25, s37, v21
	v_cmp_lt_u32_e32 vcc, 31, v20
	global_store_dwordx2 v[22:23], v[24:25], off sc1
	s_and_saveexec_b64 s[26:27], vcc
	s_cbranch_execz .LBB0_428
	v_lshl_or_b32 v18, v18, 7, v20
	v_subrev_u32_e32 v18, 32, v18
	v_and_b32_e32 v21, 0x7c, v19
	v_ashrrev_i32_e32 v19, 31, v18
	v_lshlrev_b64 v[18:19], 9, v[18:19]
	v_lshl_or_b32 v18, v21, 2, v18
	v_lshl_add_u64 v[20:21], s[10:11], 0, v[18:19]
	global_store_dwordx4 v[20:21], v[10:13], off sc0 sc1 nt
	s_nop 1
	v_lshl_add_u64 v[10:11], s[12:13], 0, v[18:19]
	global_store_dwordx4 v[10:11], v[14:17], off sc0 sc1 nt
	s_nop 1
.LBB0_428:
	s_or_b64 exec, exec, s[26:27]
	v_add_u32_e32 v13, 0xc0, v47
	v_lshlrev_b32_e32 v11, 2, v13
	v_ashrrev_i32_e32 v10, 12, v13
	v_lshrrev_b32_e32 v14, 5, v13
	v_bfe_u32 v15, v11, 6, 1
	v_lshl_or_b32 v15, v10, 1, v15
	v_bfe_u32 v14, v14, 5, 2
	v_mad_i32_i24 v14, v15, 5, v14
	v_ashrrev_i32_e32 v15, 31, v14
	v_bfe_u32 v12, v13, 5, 7
	v_lshlrev_b64 v[14:15], 12, v[14:15]
	v_bfe_u32 v13, v13, 5, 5
	v_lshl_add_u64 v[16:17], v[44:45], 0, v[14:15]
	v_lshlrev_b32_e32 v18, 4, v13
	v_mov_b32_e32 v19, v35
	v_lshl_add_u64 v[16:17], v[16:17], 0, v[18:19]
	v_bfe_u32 v18, v6, 16, 1
	v_add3_u32 v18, v6, v18, s36
	v_bfe_u32 v19, v7, 16, 1
	v_lshrrev_b32_e32 v18, 16, v18
	v_add3_u32 v19, v7, v19, s36
	v_and_or_b32 v18, v19, s37, v18
	v_bfe_u32 v19, v8, 16, 1
	v_add3_u32 v19, v8, v19, s36
	v_bfe_u32 v20, v9, 16, 1
	v_lshrrev_b32_e32 v19, 16, v19
	v_add3_u32 v20, v9, v20, s36
	v_lshl_add_u64 v[16:17], v[16:17], 0, v[34:35]
	v_and_or_b32 v19, v20, s37, v19
	global_store_dwordx2 v[16:17], v[18:19], off sc1
	v_lshl_add_u64 v[14:15], v[42:43], 0, v[14:15]
	v_lshlrev_b32_e32 v16, 6, v13
	v_mov_b32_e32 v17, v35
	v_bfe_u32 v13, v2, 16, 1
	v_lshl_add_u64 v[14:15], v[14:15], 0, v[16:17]
	v_add3_u32 v13, v2, v13, s36
	v_bfe_u32 v16, v3, 16, 1
	v_lshrrev_b32_e32 v13, 16, v13
	v_add3_u32 v16, v3, v16, s36
	v_and_or_b32 v16, v16, s37, v13
	v_bfe_u32 v13, v4, 16, 1
	v_add3_u32 v13, v4, v13, s36
	v_bfe_u32 v17, v5, 16, 1
	v_lshrrev_b32_e32 v13, 16, v13
	v_add3_u32 v17, v5, v17, s36
	v_lshl_add_u64 v[14:15], v[14:15], 0, v[36:37]
	v_and_or_b32 v17, v17, s37, v13
	v_cmp_lt_u32_e32 vcc, 31, v12
	global_store_dwordx2 v[14:15], v[16:17], off sc1
	s_and_saveexec_b64 s[26:27], vcc
	s_cbranch_execz .LBB0_430
	v_lshl_or_b32 v10, v10, 7, v12
	v_subrev_u32_e32 v10, 32, v10
	v_and_b32_e32 v13, 0x7c, v11
	v_ashrrev_i32_e32 v11, 31, v10
	v_lshlrev_b64 v[10:11], 9, v[10:11]
	v_lshl_or_b32 v10, v13, 2, v10
	v_lshl_add_u64 v[12:13], s[10:11], 0, v[10:11]
	global_store_dwordx4 v[12:13], v[6:9], off sc0 sc1 nt
	s_nop 1
	v_lshl_add_u64 v[6:7], s[12:13], 0, v[10:11]
	global_store_dwordx4 v[6:7], v[2:5], off sc0 sc1 nt
	s_nop 1

.LBB0_431:
	s_and_b64 vcc, exec, s[26:27]
	s_cbranch_vccz .LBB0_416
	s_load_dwordx4 s[28:31], s[20:21], 0x20
	s_lshl_b32 s26, s38, 10
	v_lshl_add_u32 v2, v46, 2, s26
	v_ashrrev_i32_e32 v3, 31, v2
	v_lshlrev_b64 v[2:3], 2, v[2:3]
	s_waitcnt lgkmcnt(0)
	v_lshl_add_u64 v[42:43], s[28:29], 0, v[2:3]
	v_lshl_add_u64 v[44:45], s[30:31], 0, v[2:3]
	global_load_dwordx4 v[26:29], v[42:43], off nt
	global_load_dwordx4 v[22:25], v[42:43], off offset:1024 nt
	global_load_dwordx4 v[30:33], v[44:45], off nt
	global_load_dwordx4 v[18:21], v[44:45], off offset:1024 nt
	global_load_dwordx4 v[10:13], v[42:43], off offset:2048 nt
	global_load_dwordx4 v[6:9], v[42:43], off offset:3072 nt
	global_load_dwordx4 v[14:17], v[44:45], off offset:2048 nt
	global_load_dwordx4 v[2:5], v[44:45], off offset:3072 nt
	v_lshl_add_u32 v44, s38, 8, v46
	v_mov_b32_e32 v39, v35
	v_mov_b32_e32 v41, v35
	v_lshl_add_u64 v[42:43], s[14:15], 0, v[38:39]
	v_lshl_add_u64 v[38:39], s[18:19], 0, v[40:41]
	v_lshlrev_b32_e32 v41, 2, v44
	v_ashrrev_i32_e32 v40, 16, v44
	v_lshrrev_b32_e32 v46, 7, v44
	v_bfe_u32 v50, v41, 6, 3
	v_bfe_u32 v51, v46, 5, 4
	v_lshl_or_b32 v50, v40, 3, v50
	v_mad_i32_i24 v50, v50, 17, v51
	v_ashrrev_i32_e32 v51, 31, v50
	v_bfe_u32 v48, v44, 7, 5
	v_lshlrev_b64 v[50:51], 12, v[50:51]
	v_mov_b32_e32 v47, v35
	v_mov_b32_e32 v49, v35
	v_lshlrev_b32_e32 v46, 4, v48
	v_lshlrev_b32_e32 v48, 6, v48
	v_lshl_add_u64 v[52:53], v[42:43], 0, v[50:51]
	v_lshl_add_u64 v[50:51], v[38:39], 0, v[50:51]
	v_lshl_add_u64 v[46:47], v[52:53], 0, v[46:47]
	v_lshl_add_u64 v[48:49], v[50:51], 0, v[48:49]
	v_bfe_u32 v45, v44, 7, 9
	v_mov_b32_e32 v37, v35
	v_lshl_add_u64 v[46:47], v[46:47], 0, v[34:35]
	v_cmp_lt_u32_e32 vcc, 31, v45
	v_lshl_add_u64 v[48:49], v[48:49], 0, v[36:37]
	s_waitcnt vmcnt(0)
	v_mov_b32_e32 v50, v26
	v_mov_b32_e32 v51, v22
	v_mov_b32_e32 v52, v30
	v_mov_b32_e32 v53, v18
	v_mov_b32_e32 v54, v10
	v_mov_b32_e32 v55, v6
	v_mov_b32_e32 v56, v14
	v_mov_b32_e32 v57, v2
	v_bfe_u32 v58, v26, 16, 1
	v_bfe_u32 v60, v28, 16, 1
	v_pk_add_f32 v[50:51], v[50:51], v[52:53]
	v_bfe_u32 v59, v27, 16, 1
	v_bfe_u32 v61, v29, 16, 1
	v_bfe_u32 v62, v30, 16, 1
	v_bfe_u32 v64, v32, 16, 1
	v_pk_add_f32 v[52:53], v[54:55], v[56:57]
	v_add3_u32 v54, v26, v58, s36
	v_add3_u32 v56, v28, v60, s36
	v_add_f32_e32 v50, 0, v50
	v_bfe_u32 v63, v31, 16, 1
	v_bfe_u32 v65, v33, 16, 1
	v_add3_u32 v55, v27, v59, s36
	v_add3_u32 v57, v29, v61, s36
	v_add3_u32 v58, v30, v62, s36
	v_add3_u32 v60, v32, v64, s36
	v_lshrrev_b32_e32 v54, 16, v54
	v_lshrrev_b32_e32 v56, 16, v56
	v_add_f32_e32 v62, v50, v51
	v_add3_u32 v59, v31, v63, s36
	v_add3_u32 v61, v33, v65, s36
	v_lshrrev_b32_e32 v58, 16, v58
	v_lshrrev_b32_e32 v60, 16, v60
	v_and_or_b32 v50, v55, s37, v54
	v_and_or_b32 v51, v57, s37, v56
	v_add_f32_e32 v52, v62, v52
	v_and_or_b32 v54, v59, s37, v58
	v_and_or_b32 v55, v61, s37, v60
	v_add_f32_e32 v52, v52, v53
	global_store_dwordx2 v[46:47], v[50:51], off sc1
	global_store_dwordx2 v[48:49], v[54:55], off sc1
	s_and_saveexec_b64 s[26:27], vcc
	s_cbranch_execz .LBB0_434
	v_lshl_or_b32 v40, v40, 9, v45
	v_subrev_u32_e32 v40, 32, v40
	v_and_b32_e32 v46, 0x1fc, v41
	v_ashrrev_i32_e32 v41, 31, v40
	v_lshlrev_b64 v[40:41], 11, v[40:41]
	v_lshl_or_b32 v40, v46, 2, v40
	v_lshl_add_u64 v[46:47], s[24:25], 0, v[40:41]
	global_store_dwordx4 v[46:47], v[26:29], off sc0 sc1 nt
	s_nop 1
	v_lshl_add_u64 v[26:27], s[16:17], 0, v[40:41]
	global_store_dwordx4 v[26:27], v[30:33], off sc0 sc1 nt
	s_nop 1
.LBB0_434:
	s_or_b64 exec, exec, s[26:27]
	v_add_u32_e32 v29, 64, v44
	v_lshlrev_b32_e32 v27, 2, v29
	v_ashrrev_i32_e32 v26, 16, v29
	v_lshrrev_b32_e32 v30, 7, v29
	v_bfe_u32 v31, v27, 6, 3
	v_lshl_or_b32 v31, v26, 3, v31
	v_bfe_u32 v30, v30, 5, 4
	v_mad_i32_i24 v30, v31, 17, v30
	v_ashrrev_i32_e32 v31, 31, v30
	v_bfe_u32 v28, v29, 7, 9
	v_lshlrev_b64 v[30:31], 12, v[30:31]
	v_bfe_u32 v29, v29, 7, 5
	v_lshl_add_u64 v[32:33], v[42:43], 0, v[30:31]
	v_lshlrev_b32_e32 v40, 4, v29
	v_mov_b32_e32 v41, v35
	v_lshl_add_u64 v[32:33], v[32:33], 0, v[40:41]
	v_bfe_u32 v40, v22, 16, 1
	v_add3_u32 v40, v22, v40, s36
	v_bfe_u32 v41, v23, 16, 1
	v_lshrrev_b32_e32 v40, 16, v40
	v_add3_u32 v41, v23, v41, s36
	v_and_or_b32 v40, v41, s37, v40
	v_bfe_u32 v41, v24, 16, 1
	v_add3_u32 v41, v24, v41, s36
	v_bfe_u32 v45, v25, 16, 1
	v_lshrrev_b32_e32 v41, 16, v41
	v_add3_u32 v45, v25, v45, s36
	v_lshl_add_u64 v[32:33], v[32:33], 0, v[34:35]
	v_and_or_b32 v41, v45, s37, v41
	global_store_dwordx2 v[32:33], v[40:41], off sc1
	v_lshl_add_u64 v[30:31], v[38:39], 0, v[30:31]
	v_lshlrev_b32_e32 v32, 6, v29
	v_mov_b32_e32 v33, v35
	v_bfe_u32 v29, v18, 16, 1
	v_lshl_add_u64 v[30:31], v[30:31], 0, v[32:33]
	v_add3_u32 v29, v18, v29, s36
	v_bfe_u32 v32, v19, 16, 1
	v_lshrrev_b32_e32 v29, 16, v29
	v_add3_u32 v32, v19, v32, s36
	v_and_or_b32 v32, v32, s37, v29
	v_bfe_u32 v29, v20, 16, 1
	v_add3_u32 v29, v20, v29, s36
	v_bfe_u32 v33, v21, 16, 1
	v_lshrrev_b32_e32 v29, 16, v29
	v_add3_u32 v33, v21, v33, s36
	v_lshl_add_u64 v[30:31], v[30:31], 0, v[36:37]
	v_and_or_b32 v33, v33, s37, v29
	v_cmp_lt_u32_e32 vcc, 31, v28
	global_store_dwordx2 v[30:31], v[32:33], off sc1
	s_and_saveexec_b64 s[26:27], vcc
	s_cbranch_execz .LBB0_436
	v_lshl_or_b32 v26, v26, 9, v28
	v_subrev_u32_e32 v26, 32, v26
	v_and_b32_e32 v29, 0x1fc, v27
	v_ashrrev_i32_e32 v27, 31, v26
	v_lshlrev_b64 v[26:27], 11, v[26:27]
	v_lshl_or_b32 v26, v29, 2, v26
	v_lshl_add_u64 v[28:29], s[24:25], 0, v[26:27]
	global_store_dwordx4 v[28:29], v[22:25], off sc0 sc1 nt
	s_nop 1
	v_lshl_add_u64 v[22:23], s[16:17], 0, v[26:27]
	global_store_dwordx4 v[22:23], v[18:21], off sc0 sc1 nt
	s_nop 1
.LBB0_436:
	s_or_b64 exec, exec, s[26:27]
	v_add_u32_e32 v21, 0x80, v44
	v_lshlrev_b32_e32 v19, 2, v21
	v_ashrrev_i32_e32 v18, 16, v21
	v_lshrrev_b32_e32 v22, 7, v21
	v_bfe_u32 v23, v19, 6, 3
	v_lshl_or_b32 v23, v18, 3, v23
	v_bfe_u32 v22, v22, 5, 4
	v_mad_i32_i24 v22, v23, 17, v22
	v_ashrrev_i32_e32 v23, 31, v22
	v_bfe_u32 v20, v21, 7, 9
	v_lshlrev_b64 v[22:23], 12, v[22:23]
	v_bfe_u32 v21, v21, 7, 5
	v_lshl_add_u64 v[24:25], v[42:43], 0, v[22:23]
	v_lshlrev_b32_e32 v26, 4, v21
	v_mov_b32_e32 v27, v35
	v_lshl_add_u64 v[24:25], v[24:25], 0, v[26:27]
	v_bfe_u32 v26, v10, 16, 1
	v_add3_u32 v26, v10, v26, s36
	v_bfe_u32 v27, v11, 16, 1
	v_lshrrev_b32_e32 v26, 16, v26
	v_add3_u32 v27, v11, v27, s36
	v_and_or_b32 v26, v27, s37, v26
	v_bfe_u32 v27, v12, 16, 1
	v_add3_u32 v27, v12, v27, s36
	v_bfe_u32 v28, v13, 16, 1
	v_lshrrev_b32_e32 v27, 16, v27
	v_add3_u32 v28, v13, v28, s36
	v_lshl_add_u64 v[24:25], v[24:25], 0, v[34:35]
	v_and_or_b32 v27, v28, s37, v27
	global_store_dwordx2 v[24:25], v[26:27], off sc1
	v_lshl_add_u64 v[22:23], v[38:39], 0, v[22:23]
	v_lshlrev_b32_e32 v24, 6, v21
	v_mov_b32_e32 v25, v35
	v_bfe_u32 v21, v14, 16, 1
	v_lshl_add_u64 v[22:23], v[22:23], 0, v[24:25]
	v_add3_u32 v21, v14, v21, s36
	v_bfe_u32 v24, v15, 16, 1
	v_lshrrev_b32_e32 v21, 16, v21
	v_add3_u32 v24, v15, v24, s36
	v_and_or_b32 v24, v24, s37, v21
	v_bfe_u32 v21, v16, 16, 1
	v_add3_u32 v21, v16, v21, s36
	v_bfe_u32 v25, v17, 16, 1
	v_lshrrev_b32_e32 v21, 16, v21
	v_add3_u32 v25, v17, v25, s36
	v_lshl_add_u64 v[22:23], v[22:23], 0, v[36:37]
	v_and_or_b32 v25, v25, s37, v21
	v_cmp_lt_u32_e32 vcc, 31, v20
	global_store_dwordx2 v[22:23], v[24:25], off sc1
	s_and_saveexec_b64 s[26:27], vcc
	s_cbranch_execz .LBB0_438
	v_lshl_or_b32 v18, v18, 9, v20
	v_subrev_u32_e32 v18, 32, v18
	v_and_b32_e32 v21, 0x1fc, v19
	v_ashrrev_i32_e32 v19, 31, v18
	v_lshlrev_b64 v[18:19], 11, v[18:19]
	v_lshl_or_b32 v18, v21, 2, v18
	v_lshl_add_u64 v[20:21], s[24:25], 0, v[18:19]
	global_store_dwordx4 v[20:21], v[10:13], off sc0 sc1 nt
	s_nop 1
	v_lshl_add_u64 v[10:11], s[16:17], 0, v[18:19]
	global_store_dwordx4 v[10:11], v[14:17], off sc0 sc1 nt
	s_nop 1
.LBB0_438:
	s_or_b64 exec, exec, s[26:27]
	v_add_u32_e32 v13, 0xc0, v44
	v_lshlrev_b32_e32 v11, 2, v13
	v_ashrrev_i32_e32 v10, 16, v13
	v_lshrrev_b32_e32 v14, 7, v13
	v_bfe_u32 v15, v11, 6, 3
	v_lshl_or_b32 v15, v10, 3, v15
	v_bfe_u32 v14, v14, 5, 4
	v_mad_i32_i24 v14, v15, 17, v14
	v_ashrrev_i32_e32 v15, 31, v14
	v_bfe_u32 v12, v13, 7, 9
	v_lshlrev_b64 v[14:15], 12, v[14:15]
	v_bfe_u32 v13, v13, 7, 5
	v_lshl_add_u64 v[16:17], v[42:43], 0, v[14:15]
	v_lshlrev_b32_e32 v18, 4, v13
	v_mov_b32_e32 v19, v35
	v_lshl_add_u64 v[16:17], v[16:17], 0, v[18:19]
	v_bfe_u32 v18, v6, 16, 1
	v_add3_u32 v18, v6, v18, s36
	v_bfe_u32 v19, v7, 16, 1
	v_lshrrev_b32_e32 v18, 16, v18
	v_add3_u32 v19, v7, v19, s36
	v_and_or_b32 v18, v19, s37, v18
	v_bfe_u32 v19, v8, 16, 1
	v_add3_u32 v19, v8, v19, s36
	v_bfe_u32 v20, v9, 16, 1
	v_lshrrev_b32_e32 v19, 16, v19
	v_add3_u32 v20, v9, v20, s36
	v_lshl_add_u64 v[16:17], v[16:17], 0, v[34:35]
	v_and_or_b32 v19, v20, s37, v19
	v_lshlrev_b32_e32 v34, 6, v13
	v_bfe_u32 v13, v2, 16, 1
	global_store_dwordx2 v[16:17], v[18:19], off sc1
	v_add3_u32 v13, v2, v13, s36
	v_bfe_u32 v16, v3, 16, 1
	v_lshrrev_b32_e32 v13, 16, v13
	v_add3_u32 v16, v3, v16, s36
	v_and_or_b32 v16, v16, s37, v13
	v_bfe_u32 v13, v4, 16, 1
	v_lshl_add_u64 v[14:15], v[38:39], 0, v[14:15]
	v_add3_u32 v13, v4, v13, s36
	v_bfe_u32 v17, v5, 16, 1
	v_lshl_add_u64 v[14:15], v[14:15], 0, v[34:35]
	v_lshrrev_b32_e32 v13, 16, v13
	v_add3_u32 v17, v5, v17, s36
	v_lshl_add_u64 v[14:15], v[14:15], 0, v[36:37]
	v_and_or_b32 v17, v17, s37, v13
	v_cmp_lt_u32_e32 vcc, 31, v12
	global_store_dwordx2 v[14:15], v[16:17], off sc1
	s_and_saveexec_b64 s[26:27], vcc
	s_cbranch_execz .LBB0_415
	v_lshl_or_b32 v10, v10, 9, v12
	v_subrev_u32_e32 v10, 32, v10
	v_and_b32_e32 v13, 0x1fc, v11
	v_ashrrev_i32_e32 v11, 31, v10
	v_lshlrev_b64 v[10:11], 11, v[10:11]
	v_lshl_or_b32 v10, v13, 2, v10
	v_lshl_add_u64 v[12:13], s[24:25], 0, v[10:11]
	global_store_dwordx4 v[12:13], v[6:9], off sc0 sc1 nt
	s_nop 1
	v_lshl_add_u64 v[6:7], s[16:17], 0, v[10:11]
	global_store_dwordx4 v[6:7], v[2:5], off sc0 sc1 nt
	s_nop 1
	s_branch .LBB0_415

.LBB0_1090:
	s_waitcnt vmcnt(8)
	v_and_b32_e32 v95, 0xffff0000, v26
	v_and_b32_e32 v97, 0xffff0000, v27
	v_lshlrev_b32_e32 v94, 16, v26
	v_lshlrev_b32_e32 v96, 16, v27
	v_mov_b32_e32 v100, v95
	v_mov_b32_e32 v101, v97
	v_mov_b32_e32 v98, v94
	v_mov_b32_e32 v99, v96
	v_pk_mul_f32 v[100:101], v[100:101], v[100:101]
	s_waitcnt vmcnt(7)
	v_and_b32_e32 v103, 0xffff0000, v25
	v_pk_fma_f32 v[98:99], v[98:99], v[98:99], v[100:101]
	v_and_b32_e32 v102, 0xffff0000, v24
	v_pk_add_f32 v[98:99], v[98:99], v[98:99] op_sel_hi:[0,1]
	s_waitcnt vmcnt(6)
	v_lshlrev_b32_e32 v108, 16, v23
	v_lshlrev_b32_e32 v101, 16, v25
	v_lshlrev_b32_e32 v100, 16, v24
	v_pk_mul_f32 v[104:105], v[102:103], v[102:103]
	v_lshlrev_b32_e32 v106, 16, v22
	v_and_b32_e32 v109, 0xffff0000, v23
	v_mul_f32_e32 v98, v108, v108
	v_pk_fma_f32 v[104:105], v[100:101], v[100:101], v[104:105]
	v_and_b32_e32 v107, 0xffff0000, v22
	v_pk_fma_f32 v[110:111], v[108:109], v[108:109], v[98:99] op_sel_hi:[1,1,0]
	s_waitcnt vmcnt(5)
	v_lshlrev_b32_e32 v112, 16, v20
	v_and_b32_e32 v113, 0xffff0000, v20
	v_lshlrev_b32_e32 v114, 16, v21
	v_and_b32_e32 v115, 0xffff0000, v21
	v_mul_f32_e32 v98, v106, v106
	v_pk_add_f32 v[104:105], v[104:105], v[104:105] op_sel_hi:[0,1]
	v_pk_mul_f32 v[116:117], v[112:113], v[112:113]
	v_pk_mul_f32 v[118:119], v[114:115], v[114:115]
	v_pk_fma_f32 v[120:121], v[106:107], v[106:107], v[98:99] op_sel_hi:[1,1,0]
	v_mov_b32_e32 v110, v117
	v_mov_b32_e32 v120, v116
	v_mov_b32_e32 v104, v118
	v_mov_b32_e32 v98, v119
	v_pk_add_f32 v[110:111], v[120:121], v[110:111]
	v_pk_add_f32 v[98:99], v[104:105], v[98:99]
	v_xor_b32_e32 v104, 1, v93
	v_pk_add_f32 v[98:99], v[110:111], v[98:99]
	s_waitcnt vmcnt(4)
	v_lshlrev_b32_e32 v116, 16, v53
	v_add_f32_e32 v98, v98, v99
	v_and_b32_e32 v99, 64, v93
	v_add_u32_e32 v99, 64, v99
	v_cmp_lt_i32_e32 vcc, v104, v99
	v_and_b32_e32 v117, 0xffff0000, v53
	s_nop 0
	v_cndmask_b32_e32 v104, v93, v104, vcc
	v_lshlrev_b32_e32 v104, 2, v104
	ds_bpermute_b32 v104, v104, v98
	s_waitcnt lgkmcnt(0)
	v_add_f32_e32 v98, v98, v104
	v_xor_b32_e32 v104, 2, v93
	v_cmp_lt_i32_e32 vcc, v104, v99
	s_nop 1
	v_cndmask_b32_e32 v104, v93, v104, vcc
	v_lshlrev_b32_e32 v104, 2, v104
	ds_bpermute_b32 v104, v104, v98
	s_waitcnt lgkmcnt(0)
	v_add_f32_e32 v98, v98, v104
	v_xor_b32_e32 v104, 4, v93
	v_cmp_lt_i32_e32 vcc, v104, v99
	s_nop 1
	v_cndmask_b32_e32 v104, v93, v104, vcc
	v_lshlrev_b32_e32 v104, 2, v104
	ds_bpermute_b32 v104, v104, v98
	s_waitcnt lgkmcnt(0)
	v_add_f32_e32 v98, v98, v104
	v_xor_b32_e32 v104, 8, v93
	v_cmp_lt_i32_e32 vcc, v104, v99
	s_nop 1
	v_cndmask_b32_e32 v104, v93, v104, vcc
	v_lshlrev_b32_e32 v104, 2, v104
	ds_bpermute_b32 v104, v104, v98
	s_waitcnt lgkmcnt(0)
	v_add_f32_e32 v98, v98, v104
	v_xor_b32_e32 v104, 16, v93
	v_cmp_lt_i32_e32 vcc, v104, v99
	s_nop 1
	v_cndmask_b32_e32 v104, v93, v104, vcc
	v_lshlrev_b32_e32 v104, 2, v104
	ds_bpermute_b32 v104, v104, v98
	s_waitcnt lgkmcnt(0)
	v_add_f32_e32 v98, v98, v104
	v_xor_b32_e32 v104, 32, v93
	v_cmp_lt_i32_e32 vcc, v104, v99
	s_nop 1
	v_cndmask_b32_e32 v99, v93, v104, vcc
	v_lshlrev_b32_e32 v99, 2, v99
	ds_bpermute_b32 v99, v99, v98
	s_waitcnt lgkmcnt(0)
	v_add_f32_e32 v98, v98, v99
	v_fmamk_f32 v98, v98, 0x3a800000, v89
	v_mul_f32_e32 v99, 0x4f800000, v98
	v_cmp_gt_f32_e32 vcc, s30, v98
	s_nop 1
	v_cndmask_b32_e32 v98, v98, v99, vcc
	v_sqrt_f32_e32 v99, v98
	s_nop 0
	v_add_u32_e32 v104, -1, v99
	v_fma_f32 v105, -v104, v99, v98
	v_cmp_ge_f32_e64 s[2:3], 0, v105
	v_add_u32_e32 v105, 1, v99
	s_nop 0
	v_cndmask_b32_e64 v104, v99, v104, s[2:3]
	v_fma_f32 v99, -v105, v99, v98
	v_cmp_lt_f32_e64 s[2:3], 0, v99
	s_nop 1
	v_cndmask_b32_e64 v99, v104, v105, s[2:3]
	v_mul_f32_e32 v104, 0x37800000, v99
	v_cndmask_b32_e32 v99, v99, v104, vcc
	v_cmp_class_f32_e32 vcc, v98, v91
	s_nop 1
	v_cndmask_b32_e32 v98, v99, v98, vcc
	v_div_scale_f32 v99, s[2:3], v98, v98, 1.0
	v_rcp_f32_e32 v104, v99
	s_load_dwordx2 s[2:3], s[0:1], 0xb8
	v_fma_f32 v105, -v99, v104, 1.0
	v_fmac_f32_e32 v104, v105, v104
	v_div_scale_f32 v105, vcc, 1.0, v98, 1.0
	v_mul_f32_e32 v110, v105, v104
	v_fma_f32 v111, -v99, v110, v105
	v_fmac_f32_e32 v110, v111, v104
	v_fma_f32 v99, -v99, v110, v105
	v_div_fmas_f32 v99, v99, v104, v110
	v_div_fixup_f32 v98, v99, v98, 1.0
	v_pk_mul_f32 v[96:97], v[98:99], v[96:97] op_sel_hi:[0,1]
	v_pk_mul_f32 v[94:95], v[98:99], v[94:95] op_sel_hi:[0,1]
	s_waitcnt vmcnt(1)
	v_pk_mul_f32 v[96:97], v[10:11], v[96:97]
	v_lshlrev_b32_e32 v110, 16, v52
	v_and_b32_e32 v111, 0xffff0000, v52
	v_pk_mul_f32 v[94:95], v[8:9], v[94:95]
	s_waitcnt vmcnt(0)
	v_pk_fma_f32 v[96:97], v[76:77], v[116:117], v[96:97] op_sel_hi:[0,1,1]
	v_mov_b32_e32 v116, v101
	v_mov_b32_e32 v117, v103
	v_mov_b32_e32 v101, v102
	v_pk_fma_f32 v[94:95], v[76:77], v[110:111], v[94:95] op_sel_hi:[0,1,1]
	v_pk_mul_f32 v[116:117], v[98:99], v[116:117] op_sel_hi:[0,1]
	v_pk_mul_f32 v[100:101], v[98:99], v[100:101] op_sel_hi:[0,1]
	s_waitcnt lgkmcnt(0)
	v_lshl_add_u64 v[104:105], s[2:3], 0, v[18:19]
	global_store_dwordx4 v[104:105], v[94:97], off sc0 sc1 nt
	s_nop 1
	v_lshlrev_b32_e32 v94, 16, v50
	v_and_b32_e32 v95, 0xffff0000, v50
	v_lshlrev_b32_e32 v96, 16, v51
	v_and_b32_e32 v97, 0xffff0000, v51
	v_pk_mul_f32 v[100:101], v[0:1], v[100:101]
	v_pk_mul_f32 v[102:103], v[2:3], v[116:117]
	v_pk_fma_f32 v[94:95], v[76:77], v[94:95], v[100:101] op_sel_hi:[0,1,1]
	v_pk_fma_f32 v[96:97], v[76:77], v[96:97], v[102:103] op_sel_hi:[0,1,1]
	v_pk_mul_f32 v[102:103], v[98:99], v[108:109] op_sel_hi:[0,1]
	v_pk_mul_f32 v[106:107], v[98:99], v[106:107] op_sel_hi:[0,1]
	v_lshl_add_u64 v[110:111], v[104:105], 0, s[12:13]
	global_store_dwordx4 v[110:111], v[94:97], off sc0 sc1 nt
	s_nop 1
	v_lshlrev_b32_e32 v94, 16, v48
	v_and_b32_e32 v95, 0xffff0000, v48
	v_lshlrev_b32_e32 v96, 16, v49
	v_and_b32_e32 v97, 0xffff0000, v49
	v_pk_mul_f32 v[106:107], v[4:5], v[106:107]
	v_pk_mul_f32 v[102:103], v[6:7], v[102:103]
	v_pk_fma_f32 v[94:95], v[76:77], v[94:95], v[106:107] op_sel_hi:[0,1,1]
	v_pk_fma_f32 v[96:97], v[76:77], v[96:97], v[102:103] op_sel_hi:[0,1,1]
	v_pk_mul_f32 v[102:103], v[98:99], v[114:115] op_sel_hi:[0,1]
	v_pk_mul_f32 v[98:99], v[98:99], v[112:113] op_sel_hi:[0,1]
	v_lshl_add_u64 v[100:101], v[104:105], 0, s[14:15]
	global_store_dwordx4 v[100:101], v[94:97], off sc0 sc1 nt
	s_nop 1
	v_lshlrev_b32_e32 v94, 16, v46
	v_and_b32_e32 v95, 0xffff0000, v46
	v_lshlrev_b32_e32 v96, 16, v47
	v_and_b32_e32 v97, 0xffff0000, v47
	v_pk_mul_f32 v[98:99], v[12:13], v[98:99]
	v_pk_mul_f32 v[102:103], v[14:15], v[102:103]
	v_lshl_add_u64 v[100:101], v[104:105], 0, s[16:17]
	v_pk_fma_f32 v[96:97], v[76:77], v[96:97], v[102:103] op_sel_hi:[0,1,1]
	v_pk_fma_f32 v[94:95], v[76:77], v[94:95], v[98:99] op_sel_hi:[0,1,1]
	global_store_dwordx4 v[100:101], v[94:97], off sc0 sc1 nt
	s_nop 1
.LBB0_1091:
	s_andn2_b64 vcc, exec, s[26:27]
	s_cbranch_vccnz .LBB0_1094
	s_waitcnt vmcnt(8)
	v_and_b32_e32 v95, 0xffff0000, v34
	v_and_b32_e32 v97, 0xffff0000, v35
	v_lshlrev_b32_e32 v94, 16, v34
	v_lshlrev_b32_e32 v96, 16, v35
	v_mov_b32_e32 v100, v95
	v_mov_b32_e32 v101, v97
	v_mov_b32_e32 v98, v94
	v_mov_b32_e32 v99, v96
	v_pk_mul_f32 v[100:101], v[100:101], v[100:101]
	s_waitcnt vmcnt(7)
	v_and_b32_e32 v103, 0xffff0000, v33
	v_pk_fma_f32 v[98:99], v[98:99], v[98:99], v[100:101]
	v_and_b32_e32 v102, 0xffff0000, v32
	v_pk_add_f32 v[98:99], v[98:99], v[98:99] op_sel_hi:[0,1]
	s_waitcnt vmcnt(6)
	v_lshlrev_b32_e32 v108, 16, v31
	v_lshlrev_b32_e32 v101, 16, v33
	v_lshlrev_b32_e32 v100, 16, v32
	v_pk_mul_f32 v[104:105], v[102:103], v[102:103]
	v_lshlrev_b32_e32 v106, 16, v30
	v_and_b32_e32 v109, 0xffff0000, v31
	v_mul_f32_e32 v98, v108, v108
	v_pk_fma_f32 v[104:105], v[100:101], v[100:101], v[104:105]
	v_and_b32_e32 v107, 0xffff0000, v30
	v_pk_fma_f32 v[110:111], v[108:109], v[108:109], v[98:99] op_sel_hi:[1,1,0]
	s_waitcnt vmcnt(5)
	v_lshlrev_b32_e32 v112, 16, v28
	v_and_b32_e32 v113, 0xffff0000, v28
	v_lshlrev_b32_e32 v114, 16, v29
	v_and_b32_e32 v115, 0xffff0000, v29
	v_mul_f32_e32 v98, v106, v106
	v_pk_add_f32 v[104:105], v[104:105], v[104:105] op_sel_hi:[0,1]
	v_pk_mul_f32 v[116:117], v[112:113], v[112:113]
	v_pk_mul_f32 v[118:119], v[114:115], v[114:115]
	v_pk_fma_f32 v[120:121], v[106:107], v[106:107], v[98:99] op_sel_hi:[1,1,0]
	v_mov_b32_e32 v110, v117
	v_mov_b32_e32 v120, v116
	v_mov_b32_e32 v104, v118
	v_mov_b32_e32 v98, v119
	v_pk_add_f32 v[110:111], v[120:121], v[110:111]
	v_pk_add_f32 v[98:99], v[104:105], v[98:99]
	v_xor_b32_e32 v104, 1, v93
	v_pk_add_f32 v[98:99], v[110:111], v[98:99]
	s_ashr_i32 s9, s8, 31
	v_add_f32_e32 v98, v98, v99
	v_and_b32_e32 v99, 64, v93
	v_add_u32_e32 v99, 64, v99
	v_cmp_lt_i32_e32 vcc, v104, v99
	s_lshl_b64 s[26:27], s[8:9], 12
	s_waitcnt vmcnt(4)
	v_lshlrev_b32_e32 v116, 16, v85
	v_cndmask_b32_e32 v104, v93, v104, vcc
	v_lshlrev_b32_e32 v104, 2, v104
	ds_bpermute_b32 v104, v104, v98
	v_and_b32_e32 v117, 0xffff0000, v85
	s_waitcnt lgkmcnt(0)
	v_add_f32_e32 v98, v98, v104
	v_xor_b32_e32 v104, 2, v93
	v_cmp_lt_i32_e32 vcc, v104, v99
	s_nop 1
	v_cndmask_b32_e32 v104, v93, v104, vcc
	v_lshlrev_b32_e32 v104, 2, v104
	ds_bpermute_b32 v104, v104, v98
	s_waitcnt lgkmcnt(0)
	v_add_f32_e32 v98, v98, v104
	v_xor_b32_e32 v104, 4, v93
	v_cmp_lt_i32_e32 vcc, v104, v99
	s_nop 1
	v_cndmask_b32_e32 v104, v93, v104, vcc
	v_lshlrev_b32_e32 v104, 2, v104
	ds_bpermute_b32 v104, v104, v98
	s_waitcnt lgkmcnt(0)
	v_add_f32_e32 v98, v98, v104
	v_xor_b32_e32 v104, 8, v93
	v_cmp_lt_i32_e32 vcc, v104, v99
	s_nop 1
	v_cndmask_b32_e32 v104, v93, v104, vcc
	v_lshlrev_b32_e32 v104, 2, v104
	ds_bpermute_b32 v104, v104, v98
	s_waitcnt lgkmcnt(0)
	v_add_f32_e32 v98, v98, v104
	v_xor_b32_e32 v104, 16, v93
	v_cmp_lt_i32_e32 vcc, v104, v99
	s_nop 1
	v_cndmask_b32_e32 v104, v93, v104, vcc
	v_lshlrev_b32_e32 v104, 2, v104
	ds_bpermute_b32 v104, v104, v98
	s_waitcnt lgkmcnt(0)
	v_add_f32_e32 v98, v98, v104
	v_xor_b32_e32 v104, 32, v93
	v_cmp_lt_i32_e32 vcc, v104, v99
	s_nop 1
	v_cndmask_b32_e32 v99, v93, v104, vcc
	v_lshlrev_b32_e32 v99, 2, v99
	ds_bpermute_b32 v99, v99, v98
	s_waitcnt lgkmcnt(0)
	v_add_f32_e32 v98, v98, v99
	v_fmamk_f32 v98, v98, 0x3a800000, v89
	v_mul_f32_e32 v99, 0x4f800000, v98
	v_cmp_gt_f32_e32 vcc, s30, v98
	s_nop 1
	v_cndmask_b32_e32 v98, v98, v99, vcc
	v_sqrt_f32_e32 v99, v98
	s_nop 0
	v_add_u32_e32 v104, -1, v99
	v_fma_f32 v105, -v104, v99, v98
	v_cmp_ge_f32_e64 s[2:3], 0, v105
	v_add_u32_e32 v105, 1, v99
	s_nop 0
	v_cndmask_b32_e64 v104, v99, v104, s[2:3]
	v_fma_f32 v99, -v105, v99, v98
	v_cmp_lt_f32_e64 s[2:3], 0, v99
	s_nop 1
	v_cndmask_b32_e64 v99, v104, v105, s[2:3]
	v_mul_f32_e32 v104, 0x37800000, v99
	v_cndmask_b32_e32 v99, v99, v104, vcc
	v_cmp_class_f32_e32 vcc, v98, v91
	s_nop 1
	v_cndmask_b32_e32 v98, v99, v98, vcc
	v_div_scale_f32 v99, s[2:3], v98, v98, 1.0
	v_rcp_f32_e32 v104, v99
	s_load_dwordx2 s[2:3], s[0:1], 0xb8
	v_fma_f32 v105, -v99, v104, 1.0
	v_fmac_f32_e32 v104, v105, v104
	v_div_scale_f32 v105, vcc, 1.0, v98, 1.0
	v_mul_f32_e32 v110, v105, v104
	v_fma_f32 v111, -v99, v110, v105
	v_fmac_f32_e32 v110, v111, v104
	v_fma_f32 v99, -v99, v110, v105
	v_div_fmas_f32 v99, v99, v104, v110
	v_div_fixup_f32 v98, v99, v98, 1.0
	v_pk_mul_f32 v[96:97], v[98:99], v[96:97] op_sel_hi:[0,1]
	v_pk_mul_f32 v[94:95], v[98:99], v[94:95] op_sel_hi:[0,1]
	s_waitcnt vmcnt(1)
	v_pk_mul_f32 v[96:97], v[10:11], v[96:97]
	s_waitcnt lgkmcnt(0)
	s_add_u32 s2, s2, s26
	v_lshlrev_b32_e32 v110, 16, v84
	v_and_b32_e32 v111, 0xffff0000, v84
	v_pk_mul_f32 v[94:95], v[8:9], v[94:95]
	s_waitcnt vmcnt(0)
	v_pk_fma_f32 v[96:97], v[86:87], v[116:117], v[96:97] op_sel_hi:[0,1,1]
	v_mov_b32_e32 v116, v101
	v_mov_b32_e32 v117, v103
	v_mov_b32_e32 v101, v102
	s_addc_u32 s3, s3, s27
	v_pk_fma_f32 v[94:95], v[86:87], v[110:111], v[94:95] op_sel_hi:[0,1,1]
	v_pk_mul_f32 v[116:117], v[98:99], v[116:117] op_sel_hi:[0,1]
	v_pk_mul_f32 v[100:101], v[98:99], v[100:101] op_sel_hi:[0,1]
	v_lshl_add_u64 v[104:105], v[184:185], 4, s[2:3]
	global_store_dwordx4 v[104:105], v[94:97], off sc0 sc1 nt
	s_nop 1
	v_lshlrev_b32_e32 v94, 16, v82
	v_and_b32_e32 v95, 0xffff0000, v82
	v_lshlrev_b32_e32 v96, 16, v83
	v_and_b32_e32 v97, 0xffff0000, v83
	v_pk_mul_f32 v[100:101], v[0:1], v[100:101]
	v_pk_mul_f32 v[102:103], v[2:3], v[116:117]
	v_pk_fma_f32 v[94:95], v[86:87], v[94:95], v[100:101] op_sel_hi:[0,1,1]
	v_pk_fma_f32 v[96:97], v[86:87], v[96:97], v[102:103] op_sel_hi:[0,1,1]
	v_pk_mul_f32 v[102:103], v[98:99], v[108:109] op_sel_hi:[0,1]
	v_pk_mul_f32 v[106:107], v[98:99], v[106:107] op_sel_hi:[0,1]
	v_lshl_add_u64 v[110:111], v[104:105], 0, s[12:13]
	global_store_dwordx4 v[110:111], v[94:97], off sc0 sc1 nt
	s_nop 1
	v_lshlrev_b32_e32 v94, 16, v80
	v_and_b32_e32 v95, 0xffff0000, v80
	v_lshlrev_b32_e32 v96, 16, v81
	v_and_b32_e32 v97, 0xffff0000, v81
	v_pk_mul_f32 v[106:107], v[4:5], v[106:107]
	v_pk_mul_f32 v[102:103], v[6:7], v[102:103]
	v_pk_fma_f32 v[94:95], v[86:87], v[94:95], v[106:107] op_sel_hi:[0,1,1]
	v_pk_fma_f32 v[96:97], v[86:87], v[96:97], v[102:103] op_sel_hi:[0,1,1]
	v_pk_mul_f32 v[102:103], v[98:99], v[114:115] op_sel_hi:[0,1]
	v_pk_mul_f32 v[98:99], v[98:99], v[112:113] op_sel_hi:[0,1]
	v_lshl_add_u64 v[100:101], v[104:105], 0, s[14:15]
	global_store_dwordx4 v[100:101], v[94:97], off sc0 sc1 nt
	s_nop 1
	v_lshlrev_b32_e32 v94, 16, v78
	v_and_b32_e32 v95, 0xffff0000, v78
	v_lshlrev_b32_e32 v96, 16, v79
	v_and_b32_e32 v97, 0xffff0000, v79
	v_pk_mul_f32 v[98:99], v[12:13], v[98:99]
	v_pk_mul_f32 v[102:103], v[14:15], v[102:103]
	v_lshl_add_u64 v[100:101], v[104:105], 0, s[16:17]
	v_pk_fma_f32 v[96:97], v[86:87], v[96:97], v[102:103] op_sel_hi:[0,1,1]
	v_pk_fma_f32 v[94:95], v[86:87], v[94:95], v[98:99] op_sel_hi:[0,1,1]
	global_store_dwordx4 v[100:101], v[94:97], off sc0 sc1 nt
	s_nop 1
	s_andn2_b64 vcc, exec, s[24:25]
	s_cbranch_vccz .LBB0_1095

.LBB0_1095:
	s_waitcnt vmcnt(7)
	v_and_b32_e32 v95, 0xffff0000, v38
	v_and_b32_e32 v97, 0xffff0000, v39
	v_lshlrev_b32_e32 v94, 16, v38
	v_lshlrev_b32_e32 v96, 16, v39
	v_mov_b32_e32 v100, v95
	v_mov_b32_e32 v101, v97
	v_mov_b32_e32 v98, v94
	v_mov_b32_e32 v99, v96
	v_pk_mul_f32 v[100:101], v[100:101], v[100:101]
	s_waitcnt vmcnt(3)
	v_and_b32_e32 v103, 0xffff0000, v59
	v_pk_fma_f32 v[98:99], v[98:99], v[98:99], v[100:101]
	v_and_b32_e32 v102, 0xffff0000, v58
	v_pk_add_f32 v[98:99], v[98:99], v[98:99] op_sel_hi:[0,1]
	s_waitcnt vmcnt(2)
	v_lshlrev_b32_e32 v108, 16, v57
	v_lshlrev_b32_e32 v101, 16, v59
	v_lshlrev_b32_e32 v100, 16, v58
	v_pk_mul_f32 v[104:105], v[102:103], v[102:103]
	v_lshlrev_b32_e32 v106, 16, v56
	v_and_b32_e32 v109, 0xffff0000, v57
	v_mul_f32_e32 v98, v108, v108
	v_pk_fma_f32 v[104:105], v[100:101], v[100:101], v[104:105]
	v_and_b32_e32 v107, 0xffff0000, v56
	v_pk_fma_f32 v[110:111], v[108:109], v[108:109], v[98:99] op_sel_hi:[1,1,0]
	s_waitcnt vmcnt(1)
	v_lshlrev_b32_e32 v112, 16, v54
	v_and_b32_e32 v113, 0xffff0000, v54
	v_lshlrev_b32_e32 v114, 16, v55
	v_and_b32_e32 v115, 0xffff0000, v55
	v_mul_f32_e32 v98, v106, v106
	v_pk_add_f32 v[104:105], v[104:105], v[104:105] op_sel_hi:[0,1]
	v_pk_mul_f32 v[116:117], v[112:113], v[112:113]
	v_pk_mul_f32 v[118:119], v[114:115], v[114:115]
	v_pk_fma_f32 v[120:121], v[106:107], v[106:107], v[98:99] op_sel_hi:[1,1,0]
	v_mov_b32_e32 v110, v117
	v_mov_b32_e32 v120, v116
	v_mov_b32_e32 v104, v118
	v_mov_b32_e32 v98, v119
	v_pk_add_f32 v[110:111], v[120:121], v[110:111]
	v_pk_add_f32 v[98:99], v[104:105], v[98:99]
	v_xor_b32_e32 v104, 1, v93
	v_pk_add_f32 v[98:99], v[110:111], v[98:99]
	s_load_dwordx2 s[24:25], s[0:1], 0xb8
	v_add_f32_e32 v98, v98, v99
	v_and_b32_e32 v99, 64, v93
	v_add_u32_e32 v99, 64, v99
	v_cmp_lt_i32_e32 vcc, v104, v99
	v_lshlrev_b32_e32 v116, 16, v69
	v_and_b32_e32 v117, 0xffff0000, v69
	v_cndmask_b32_e32 v104, v93, v104, vcc
	v_lshlrev_b32_e32 v104, 2, v104
	ds_bpermute_b32 v104, v104, v98
	s_waitcnt lgkmcnt(0)
	v_add_f32_e32 v98, v98, v104
	v_xor_b32_e32 v104, 2, v93
	v_cmp_lt_i32_e32 vcc, v104, v99
	s_nop 1
	v_cndmask_b32_e32 v104, v93, v104, vcc
	v_lshlrev_b32_e32 v104, 2, v104
	ds_bpermute_b32 v104, v104, v98
	s_waitcnt lgkmcnt(0)
	v_add_f32_e32 v98, v98, v104
	v_xor_b32_e32 v104, 4, v93
	v_cmp_lt_i32_e32 vcc, v104, v99
	s_nop 1
	v_cndmask_b32_e32 v104, v93, v104, vcc
	v_lshlrev_b32_e32 v104, 2, v104
	ds_bpermute_b32 v104, v104, v98
	s_waitcnt lgkmcnt(0)
	v_add_f32_e32 v98, v98, v104
	v_xor_b32_e32 v104, 8, v93
	v_cmp_lt_i32_e32 vcc, v104, v99
	s_nop 1
	v_cndmask_b32_e32 v104, v93, v104, vcc
	v_lshlrev_b32_e32 v104, 2, v104
	ds_bpermute_b32 v104, v104, v98
	s_waitcnt lgkmcnt(0)
	v_add_f32_e32 v98, v98, v104
	v_xor_b32_e32 v104, 16, v93
	v_cmp_lt_i32_e32 vcc, v104, v99
	s_nop 1
	v_cndmask_b32_e32 v104, v93, v104, vcc
	v_lshlrev_b32_e32 v104, 2, v104
	ds_bpermute_b32 v104, v104, v98
	s_waitcnt lgkmcnt(0)
	v_add_f32_e32 v98, v98, v104
	v_xor_b32_e32 v104, 32, v93
	v_cmp_lt_i32_e32 vcc, v104, v99
	s_nop 1
	v_cndmask_b32_e32 v99, v93, v104, vcc
	v_lshlrev_b32_e32 v99, 2, v99
	ds_bpermute_b32 v99, v99, v98
	s_waitcnt lgkmcnt(0)
	v_add_f32_e32 v98, v98, v99
	v_fmamk_f32 v98, v98, 0x3a800000, v89
	v_mul_f32_e32 v99, 0x4f800000, v98
	v_cmp_gt_f32_e32 vcc, s30, v98
	s_nop 1
	v_cndmask_b32_e32 v98, v98, v99, vcc
	v_sqrt_f32_e32 v99, v98
	s_nop 0
	v_add_u32_e32 v104, -1, v99
	v_fma_f32 v105, -v104, v99, v98
	v_cmp_ge_f32_e64 s[2:3], 0, v105
	v_add_u32_e32 v105, 1, v99
	s_nop 0
	v_cndmask_b32_e64 v104, v99, v104, s[2:3]
	v_fma_f32 v99, -v105, v99, v98
	v_cmp_lt_f32_e64 s[2:3], 0, v99
	s_nop 1
	v_cndmask_b32_e64 v99, v104, v105, s[2:3]
	v_mul_f32_e32 v104, 0x37800000, v99
	v_cndmask_b32_e32 v99, v99, v104, vcc
	v_cmp_class_f32_e32 vcc, v98, v91
	s_nop 1
	v_cndmask_b32_e32 v98, v99, v98, vcc
	v_div_scale_f32 v99, s[2:3], v98, v98, 1.0
	v_rcp_f32_e32 v104, v99
	s_add_i32 s2, s8, 1
	s_ashr_i32 s3, s2, 31
	s_lshl_b64 s[2:3], s[2:3], 12
	v_fma_f32 v105, -v99, v104, 1.0
	v_fmac_f32_e32 v104, v105, v104
	v_div_scale_f32 v105, vcc, 1.0, v98, 1.0
	v_mul_f32_e32 v110, v105, v104
	v_fma_f32 v111, -v99, v110, v105
	v_fmac_f32_e32 v110, v111, v104
	v_fma_f32 v99, -v99, v110, v105
	v_div_fmas_f32 v99, v99, v104, v110
	v_div_fixup_f32 v98, v99, v98, 1.0
	v_pk_mul_f32 v[96:97], v[98:99], v[96:97] op_sel_hi:[0,1]
	v_pk_mul_f32 v[94:95], v[98:99], v[94:95] op_sel_hi:[0,1]
	v_pk_mul_f32 v[96:97], v[10:11], v[96:97]
	s_add_u32 s2, s24, s2
	v_lshlrev_b32_e32 v110, 16, v68
	v_and_b32_e32 v111, 0xffff0000, v68
	v_pk_mul_f32 v[94:95], v[8:9], v[94:95]
	s_waitcnt vmcnt(0)
	v_pk_fma_f32 v[96:97], v[90:91], v[116:117], v[96:97] op_sel_hi:[0,1,1]
	v_mov_b32_e32 v116, v101
	v_mov_b32_e32 v117, v103
	v_mov_b32_e32 v101, v102
	s_addc_u32 s3, s25, s3
	v_pk_fma_f32 v[94:95], v[90:91], v[110:111], v[94:95] op_sel_hi:[0,1,1]
	v_pk_mul_f32 v[116:117], v[98:99], v[116:117] op_sel_hi:[0,1]
	v_pk_mul_f32 v[100:101], v[98:99], v[100:101] op_sel_hi:[0,1]
	v_lshl_add_u64 v[104:105], v[184:185], 4, s[2:3]
	global_store_dwordx4 v[104:105], v[94:97], off sc0 sc1 nt
	s_nop 1
	v_lshlrev_b32_e32 v94, 16, v74
	v_and_b32_e32 v95, 0xffff0000, v74
	v_lshlrev_b32_e32 v96, 16, v75
	v_and_b32_e32 v97, 0xffff0000, v75
	v_pk_mul_f32 v[100:101], v[0:1], v[100:101]
	v_pk_mul_f32 v[102:103], v[2:3], v[116:117]
	v_pk_fma_f32 v[94:95], v[90:91], v[94:95], v[100:101] op_sel_hi:[0,1,1]
	v_pk_fma_f32 v[96:97], v[90:91], v[96:97], v[102:103] op_sel_hi:[0,1,1]
	v_pk_mul_f32 v[102:103], v[98:99], v[108:109] op_sel_hi:[0,1]
	v_pk_mul_f32 v[106:107], v[98:99], v[106:107] op_sel_hi:[0,1]
	v_lshl_add_u64 v[110:111], v[104:105], 0, s[12:13]
	global_store_dwordx4 v[110:111], v[94:97], off sc0 sc1 nt
	s_nop 1
	v_lshlrev_b32_e32 v94, 16, v72
	v_and_b32_e32 v95, 0xffff0000, v72
	v_lshlrev_b32_e32 v96, 16, v73
	v_and_b32_e32 v97, 0xffff0000, v73
	v_pk_mul_f32 v[106:107], v[4:5], v[106:107]
	v_pk_mul_f32 v[102:103], v[6:7], v[102:103]
	v_pk_fma_f32 v[94:95], v[90:91], v[94:95], v[106:107] op_sel_hi:[0,1,1]
	v_pk_fma_f32 v[96:97], v[90:91], v[96:97], v[102:103] op_sel_hi:[0,1,1]
	v_pk_mul_f32 v[102:103], v[98:99], v[114:115] op_sel_hi:[0,1]
	v_pk_mul_f32 v[98:99], v[98:99], v[112:113] op_sel_hi:[0,1]
	v_lshl_add_u64 v[100:101], v[104:105], 0, s[14:15]
	global_store_dwordx4 v[100:101], v[94:97], off sc0 sc1 nt
	s_nop 1
	v_lshlrev_b32_e32 v94, 16, v70
	v_and_b32_e32 v95, 0xffff0000, v70
	v_lshlrev_b32_e32 v96, 16, v71
	v_and_b32_e32 v97, 0xffff0000, v71
	v_pk_mul_f32 v[98:99], v[12:13], v[98:99]
	v_pk_mul_f32 v[102:103], v[14:15], v[102:103]
	v_lshl_add_u64 v[100:101], v[104:105], 0, s[16:17]
	v_pk_fma_f32 v[96:97], v[90:91], v[96:97], v[102:103] op_sel_hi:[0,1,1]
	v_pk_fma_f32 v[94:95], v[90:91], v[94:95], v[98:99] op_sel_hi:[0,1,1]
	global_store_dwordx4 v[100:101], v[94:97], off sc0 sc1 nt
	s_nop 1
	s_andn2_b64 vcc, exec, s[22:23]
	s_cbranch_vccnz .LBB0_1080
.LBB0_1096:
	s_waitcnt vmcnt(7)
	v_and_b32_e32 v95, 0xffff0000, v36
	v_and_b32_e32 v97, 0xffff0000, v37
	v_lshlrev_b32_e32 v94, 16, v36
	v_lshlrev_b32_e32 v96, 16, v37
	v_mov_b32_e32 v100, v95
	v_mov_b32_e32 v101, v97
	v_mov_b32_e32 v98, v94
	v_mov_b32_e32 v99, v96
	v_pk_mul_f32 v[100:101], v[100:101], v[100:101]
	s_waitcnt vmcnt(3)
	v_and_b32_e32 v103, 0xffff0000, v45
	v_pk_fma_f32 v[98:99], v[98:99], v[98:99], v[100:101]
	v_and_b32_e32 v102, 0xffff0000, v44
	v_pk_add_f32 v[98:99], v[98:99], v[98:99] op_sel_hi:[0,1]
	s_waitcnt vmcnt(2)
	v_lshlrev_b32_e32 v108, 16, v43
	v_lshlrev_b32_e32 v101, 16, v45
	v_lshlrev_b32_e32 v100, 16, v44
	v_pk_mul_f32 v[104:105], v[102:103], v[102:103]
	v_lshlrev_b32_e32 v106, 16, v42
	v_and_b32_e32 v109, 0xffff0000, v43
	v_mul_f32_e32 v98, v108, v108
	v_pk_fma_f32 v[104:105], v[100:101], v[100:101], v[104:105]
	v_and_b32_e32 v107, 0xffff0000, v42
	v_pk_fma_f32 v[110:111], v[108:109], v[108:109], v[98:99] op_sel_hi:[1,1,0]
	s_waitcnt vmcnt(1)
	v_lshlrev_b32_e32 v112, 16, v40
	v_and_b32_e32 v113, 0xffff0000, v40
	v_lshlrev_b32_e32 v114, 16, v41
	v_and_b32_e32 v115, 0xffff0000, v41
	v_mul_f32_e32 v98, v106, v106
	v_pk_add_f32 v[104:105], v[104:105], v[104:105] op_sel_hi:[0,1]
	v_pk_mul_f32 v[116:117], v[112:113], v[112:113]
	v_pk_mul_f32 v[118:119], v[114:115], v[114:115]
	v_pk_fma_f32 v[120:121], v[106:107], v[106:107], v[98:99] op_sel_hi:[1,1,0]
	v_mov_b32_e32 v110, v117
	v_mov_b32_e32 v120, v116
	v_mov_b32_e32 v104, v118
	v_mov_b32_e32 v98, v119
	v_pk_add_f32 v[110:111], v[120:121], v[110:111]
	v_pk_add_f32 v[98:99], v[104:105], v[98:99]
	v_xor_b32_e32 v104, 1, v93
	v_pk_add_f32 v[98:99], v[110:111], v[98:99]
	s_load_dwordx2 s[22:23], s[0:1], 0xb8
	v_add_f32_e32 v98, v98, v99
	v_and_b32_e32 v99, 64, v93
	v_add_u32_e32 v99, 64, v99
	v_cmp_lt_i32_e32 vcc, v104, v99
	v_lshlrev_b32_e32 v116, 16, v61
	v_and_b32_e32 v117, 0xffff0000, v61
	v_cndmask_b32_e32 v104, v93, v104, vcc
	v_lshlrev_b32_e32 v104, 2, v104
	ds_bpermute_b32 v104, v104, v98
	v_and_b32_e32 v111, 0xffff0000, v60
	s_waitcnt lgkmcnt(0)
	v_add_f32_e32 v98, v98, v104
	v_xor_b32_e32 v104, 2, v93
	v_cmp_lt_i32_e32 vcc, v104, v99
	s_nop 1
	v_cndmask_b32_e32 v104, v93, v104, vcc
	v_lshlrev_b32_e32 v104, 2, v104
	ds_bpermute_b32 v104, v104, v98
	s_waitcnt lgkmcnt(0)
	v_add_f32_e32 v98, v98, v104
	v_xor_b32_e32 v104, 4, v93
	v_cmp_lt_i32_e32 vcc, v104, v99
	s_nop 1
	v_cndmask_b32_e32 v104, v93, v104, vcc
	v_lshlrev_b32_e32 v104, 2, v104
	ds_bpermute_b32 v104, v104, v98
	s_waitcnt lgkmcnt(0)
	v_add_f32_e32 v98, v98, v104
	v_xor_b32_e32 v104, 8, v93
	v_cmp_lt_i32_e32 vcc, v104, v99
	s_nop 1
	v_cndmask_b32_e32 v104, v93, v104, vcc
	v_lshlrev_b32_e32 v104, 2, v104
	ds_bpermute_b32 v104, v104, v98
	s_waitcnt lgkmcnt(0)
	v_add_f32_e32 v98, v98, v104
	v_xor_b32_e32 v104, 16, v93
	v_cmp_lt_i32_e32 vcc, v104, v99
	s_nop 1
	v_cndmask_b32_e32 v104, v93, v104, vcc
	v_lshlrev_b32_e32 v104, 2, v104
	ds_bpermute_b32 v104, v104, v98
	s_waitcnt lgkmcnt(0)
	v_add_f32_e32 v98, v98, v104
	v_xor_b32_e32 v104, 32, v93
	v_cmp_lt_i32_e32 vcc, v104, v99
	s_nop 1
	v_cndmask_b32_e32 v93, v93, v104, vcc
	v_lshlrev_b32_e32 v93, 2, v93
	ds_bpermute_b32 v93, v93, v98
	s_waitcnt lgkmcnt(0)
	v_add_f32_e32 v93, v98, v93
	v_fmamk_f32 v93, v93, 0x3a800000, v89
	v_mul_f32_e32 v98, 0x4f800000, v93
	v_cmp_gt_f32_e32 vcc, s30, v93
	s_nop 1
	v_cndmask_b32_e32 v93, v93, v98, vcc
	v_sqrt_f32_e32 v98, v93
	s_nop 0
	v_add_u32_e32 v99, -1, v98
	v_fma_f32 v104, -v99, v98, v93
	v_cmp_ge_f32_e64 s[2:3], 0, v104
	v_add_u32_e32 v104, 1, v98
	s_nop 0
	v_cndmask_b32_e64 v99, v98, v99, s[2:3]
	v_fma_f32 v98, -v104, v98, v93
	v_cmp_lt_f32_e64 s[2:3], 0, v98
	s_nop 1
	v_cndmask_b32_e64 v98, v99, v104, s[2:3]
	v_mul_f32_e32 v99, 0x37800000, v98
	v_cndmask_b32_e32 v98, v98, v99, vcc
	v_cmp_class_f32_e32 vcc, v93, v91
	s_nop 1
	v_cndmask_b32_e32 v93, v98, v93, vcc
	v_div_scale_f32 v98, s[2:3], v93, v93, 1.0
	v_rcp_f32_e32 v99, v98
	s_add_i32 s2, s8, 2
	s_ashr_i32 s3, s2, 31
	s_lshl_b64 s[2:3], s[2:3], 12
	v_fma_f32 v104, -v98, v99, 1.0
	v_fmac_f32_e32 v99, v104, v99
	v_div_scale_f32 v104, vcc, 1.0, v93, 1.0
	v_mul_f32_e32 v105, v104, v99
	v_fma_f32 v110, -v98, v105, v104
	v_fmac_f32_e32 v105, v110, v99
	v_fma_f32 v98, -v98, v105, v104
	v_div_fmas_f32 v98, v98, v99, v105
	v_div_fixup_f32 v98, v98, v93, 1.0
	v_pk_mul_f32 v[96:97], v[98:99], v[96:97] op_sel_hi:[0,1]
	v_pk_mul_f32 v[94:95], v[98:99], v[94:95] op_sel_hi:[0,1]
	v_pk_mul_f32 v[96:97], v[10:11], v[96:97]
	s_add_u32 s2, s22, s2
	v_lshlrev_b32_e32 v110, 16, v60
	v_pk_mul_f32 v[94:95], v[8:9], v[94:95]
	s_waitcnt vmcnt(0)
	v_pk_fma_f32 v[96:97], v[88:89], v[116:117], v[96:97] op_sel_hi:[0,1,1]
	v_mov_b32_e32 v116, v101
	v_mov_b32_e32 v117, v103
	v_mov_b32_e32 v101, v102
	s_addc_u32 s3, s23, s3
	v_pk_fma_f32 v[94:95], v[88:89], v[110:111], v[94:95] op_sel_hi:[0,1,1]
	v_pk_mul_f32 v[116:117], v[98:99], v[116:117] op_sel_hi:[0,1]
	v_pk_mul_f32 v[100:101], v[98:99], v[100:101] op_sel_hi:[0,1]
	v_lshl_add_u64 v[104:105], v[184:185], 4, s[2:3]
	global_store_dwordx4 v[104:105], v[94:97], off sc0 sc1 nt
	s_nop 1
	v_lshlrev_b32_e32 v94, 16, v66
	v_and_b32_e32 v95, 0xffff0000, v66
	v_lshlrev_b32_e32 v96, 16, v67
	v_and_b32_e32 v97, 0xffff0000, v67
	v_pk_mul_f32 v[100:101], v[0:1], v[100:101]
	v_pk_mul_f32 v[102:103], v[2:3], v[116:117]
	v_pk_fma_f32 v[94:95], v[88:89], v[94:95], v[100:101] op_sel_hi:[0,1,1]
	v_pk_fma_f32 v[96:97], v[88:89], v[96:97], v[102:103] op_sel_hi:[0,1,1]
	v_pk_mul_f32 v[102:103], v[98:99], v[108:109] op_sel_hi:[0,1]
	v_pk_mul_f32 v[106:107], v[98:99], v[106:107] op_sel_hi:[0,1]
	v_lshl_add_u64 v[110:111], v[104:105], 0, s[12:13]
	global_store_dwordx4 v[110:111], v[94:97], off sc0 sc1 nt
	s_nop 1
	v_lshlrev_b32_e32 v94, 16, v64
	v_and_b32_e32 v95, 0xffff0000, v64
	v_lshlrev_b32_e32 v96, 16, v65
	v_and_b32_e32 v97, 0xffff0000, v65
	v_pk_mul_f32 v[106:107], v[4:5], v[106:107]
	v_pk_mul_f32 v[102:103], v[6:7], v[102:103]
	v_pk_fma_f32 v[94:95], v[88:89], v[94:95], v[106:107] op_sel_hi:[0,1,1]
	v_pk_fma_f32 v[96:97], v[88:89], v[96:97], v[102:103] op_sel_hi:[0,1,1]
	v_pk_mul_f32 v[102:103], v[98:99], v[114:115] op_sel_hi:[0,1]
	v_pk_mul_f32 v[98:99], v[98:99], v[112:113] op_sel_hi:[0,1]
	v_lshl_add_u64 v[100:101], v[104:105], 0, s[14:15]
	global_store_dwordx4 v[100:101], v[94:97], off sc0 sc1 nt
	s_nop 1
	v_lshlrev_b32_e32 v94, 16, v62
	v_and_b32_e32 v95, 0xffff0000, v62
	v_lshlrev_b32_e32 v96, 16, v63
	v_and_b32_e32 v97, 0xffff0000, v63
	v_pk_mul_f32 v[98:99], v[12:13], v[98:99]
	v_pk_mul_f32 v[102:103], v[14:15], v[102:103]
	v_lshl_add_u64 v[100:101], v[104:105], 0, s[16:17]
	v_pk_fma_f32 v[96:97], v[88:89], v[96:97], v[102:103] op_sel_hi:[0,1,1]
	v_pk_fma_f32 v[94:95], v[88:89], v[94:95], v[98:99] op_sel_hi:[0,1,1]
	global_store_dwordx4 v[100:101], v[94:97], off sc0 sc1 nt
	s_nop 1
	s_branch .LBB0_1080
